# phase+3: attention sections first, causal-conv last (XBCV stays in Infinity Cache for the SSD phase)
# speedup vs baseline: 1.0056x; 1.0038x over previous
; #define SUB(k, bit) (!(kargs()->li == 1 && (k) == lo) || ((kargs()->submask >> (bit)) & 1u))
; __global__ void __launch_bounds__(NWAVES * 64, 2) fwd(Args args_unused) {
;     ...
;         if (IN(pb + 3)) {
;             PH_PTRS PH_LAYER
;             if (SUB(pb + 3, 0)) {
;                 const int nitems = (M / 16) * 5;
; #pragma unroll 1
;                 for (int it = gw; it < nitems; it += NGW) {
;                     const int seg = it / 5, c = (it - seg * 5) * 64 + lane;
;                     if (c >= 192 && seg * 16 < NPROMPT) continue;
;                     const bool isB = c < 192; const int col = isB ? 8 * c : 8 * (c - 192); const int zc = isB ? ZXBC + col : ZXC + col; const int nch = isB ? 1536 : 1024;
;                     const float* cwp = (isB ? A->in[I_CBW] + (size_t)l * 4 * 1536 : A->in[I_CCW] + (size_t)l * 4 * 1024) + col;
;                     const float* cbp = (isB ? A->in[I_CBB] + (size_t)l * 1536 : A->in[I_CCB] + (size_t)l * 1024) + col;
.LBB0_1364:
	s_mov_b32 s98, 0
.Lro_again_0:
	s_cmp_lt_i32 s84, 7
	s_cselect_b64 s[0:1], -1, 0
	s_cmp_gt_i32 s85, 6
	s_waitcnt lgkmcnt(0)
	s_cselect_b64 s[4:5], -1, 0
	s_and_b64 s[0:1], s[0:1], s[4:5]
	s_andn2_b64 vcc, exec, s[0:1]
	s_cbranch_vccnz .LBB0_1520
	s_mov_b64 s[26:27], s[82:83]
	s_load_dwordx2 s[28:29], s[26:27], 0x148
	s_mov_b32 s62, 0
	s_load_dword s64, s[82:83], 0x168
	v_readlane_b32 s33, v254, 3
	s_mov_b32 s3, s2
	v_mov_b32_e32 v1, v0
	s_waitcnt lgkmcnt(0)
	s_lshl_b32 s4, s33, 3
	v_readfirstlane_b32 s61, v1
	s_ashr_i32 s63, s61, 6
	s_lshl_b32 s3, s64, 3
	s_add_i32 s60, s63, s4
	s_add_u32 s30, s28, 0x1d200000
	s_addc_u32 s31, s29, 0
	s_cmpk_gt_i32 s60, 0x284f
	v_and_b32_e32 v130, 63, v1
	s_cselect_b32 s99, 1, 0
	s_cmp_eq_u32 s98, 0
	s_cbranch_scc1 .LBB0_1477
	s_cmp_lg_u32 s99, 0
	s_cbranch_scc1 .LBB0_1477
	s_add_u32 s8, s28, 0x4d800000
	s_addc_u32 s9, s29, 0
	s_add_u32 s10, s28, 0x53900000
	s_addc_u32 s11, s29, 0
	s_lshl_b32 s4, s33, 9
	s_lshl_b32 s5, s63, 6
	s_add_i32 s4, s4, s5
	v_or_b32_e32 v131, s4, v130
	v_lshlrev_b32_e32 v140, 3, v131
	s_lshl_b32 s65, s64, 12
	s_lshl_b32 s66, s64, 9
	s_movk_i32 s67, 0xc0
	s_movk_i32 s68, 0xbf
	v_mov_b32_e32 v133, 0
	v_mov_b32_e32 v141, 0x400
	v_mov_b32_e32 v142, 0x600
	v_mov_b32_e32 v143, 0x1c00
	v_mov_b32_e32 v144, 0x1600
	v_mov_b32_e32 v145, 0xd8
	v_mov_b32_e32 v146, 0xa0
	v_mov_b32_e32 v147, 0xe0
	v_mov_b32_e32 v148, 0xa8
	v_mov_b32_e32 v149, 0xc00
	s_mov_b32 s69, s60
	s_branch .LBB0_1368

; #define LAS __attribute__((address_space(3)))
; __global__ void __launch_bounds__(NWAVES * 64, 2) fwd(Args args_unused) {
;     ...
;                 LAS unsigned char* KB0 = lds; LAS unsigned char* VB0 = lds + 65536; LAS float* bsm = (LAS float*)(lds + 131072);
;                 const int qq = lane & 15, q4 = lane >> 4, w = wave;
;                 constexpr int NUN = 16 * 3 * 8 * 16;
;     ...
;                 bf16x8 qn[2] = {(bf16x8){0, 0, 0, 0, 0, 0, 0, 0}, (bf16x8){0, 0, 0, 0, 0, 0, 0, 0}}; float bnx = 0.f;
;                 __syncthreads();
;                 if (vcu < NUN) ATT_ISSUE(vcu, 0, qn);
.LBB0_1477:
	s_cmp_eq_u32 s98, 1
	s_cbranch_scc1 .Lro_fin_0
	s_add_u32 s34, s28, 0xb800000
	s_addc_u32 s35, s29, 0
	s_add_u32 s36, s28, 0x67c00000
	s_addc_u32 s37, s29, 0
	s_cmpk_lt_i32 s33, 0x1800
	s_waitcnt vmcnt(0)
	s_barrier
	s_cbranch_scc0 .LBB0_1496
	s_add_i32 s46, s62, 0x10000
	s_add_u32 s38, s28, 0xb000000
	s_addc_u32 s39, s29, 0
	s_ashr_i32 s4, s33, 7
	s_mul_hi_i32 s6, s4, 0x55555556
	s_lshr_b32 s7, s6, 31
	s_add_i32 s6, s6, s7
	s_mul_i32 s6, s6, 3
	s_sub_i32 s9, s4, s6
	s_mul_hi_i32 s4, s33, 0x2aaaaaab
	s_lshr_b32 s6, s4, 31
	s_ashr_i32 s4, s4, 6
	s_and_b32 s5, s33, 15
	s_bfe_u32 s8, s33, 0x30004
	s_add_i32 s4, s4, s6
	s_cmp_eq_u32 s9, 1
	s_cselect_b32 s6, 2, 4
	s_cmp_lg_u32 s9, 0
	s_cselect_b32 s12, s6, 0
	s_sub_i32 s7, 4, s12
	v_lshrrev_b32_e32 v4, 3, v130
	s_lshr_b32 s6, 16, s12
	s_lshr_b32 s13, s5, s7
	v_bitop3_b32 v5, v4, v1, 7 bitop3:0x78
	s_lshl_b32 s10, s9, 9
	s_lshl_b32 s15, s8, 6
	s_mul_i32 s6, s13, s6
	s_or_b32 s16, s10, s15
	v_lshlrev_b32_e32 v29, 3, v5
	s_sub_i32 s5, s5, s6
	v_or_b32_e32 v5, s16, v29
	s_lshl_b32 s14, s5, 7
	v_or_b32_e32 v28, 0xffffff80, v4
	v_add_u32_e32 v4, 0x600, v5
	v_mov_b32_e32 v30, 0xf8
	v_add_u32_e32 v12, s14, v28
	v_lshrrev_b32_e32 v13, 8, v4
	v_bitop3_b32 v4, s16, v30, v29 bitop3:0xc8
	s_lshl_b32 s47, s63, 3
	s_ashr_i32 s5, s4, 31
	v_lshlrev_b32_e32 v6, 1, v4
	v_mov_b32_e32 v4, 0
	v_add_u32_e32 v8, s47, v12
	s_lshl_b64 s[4:5], s[4:5], 11
	v_max_i32_e32 v8, 0, v8
	v_mov_b32_e32 v9, v4
	s_or_b32 s6, s4, s13
	s_mov_b32 s7, s5
	v_lshlrev_b64 v[8:9], s12, v[8:9]
	v_add_u32_e32 v5, 0xc00, v5
	v_lshl_add_u64 v[8:9], s[6:7], 0, v[8:9]
	s_mov_b32 s48, 0x8100
	v_mov_b32_e32 v7, v4
	v_lshrrev_b32_e32 v5, 8, v5
	v_mad_u64_u32 v[10:11], s[10:11], v13, s48, v[8:9]
	v_lshl_add_u64 v[6:7], s[30:31], 0, v[6:7]
	v_lshlrev_b64 v[10:11], 9, v[10:11]
	s_lshl_b32 s49, s63, 10
	v_mad_u64_u32 v[8:9], s[10:11], v5, s48, v[8:9]
	v_lshl_add_u64 v[10:11], v[6:7], 0, v[10:11]
	s_add_i32 m0, s62, s49
	v_lshlrev_b64 v[8:9], 9, v[8:9]
	s_add_i32 s24, s63, 8
	global_load_lds_dwordx4 v[10:11], off
	v_lshl_add_u64 v[8:9], v[6:7], 0, v[8:9]
	s_add_i32 m0, s46, s49
	s_lshl_b32 s50, s24, 3
	global_load_lds_dwordx4 v[8:9], off
	v_add_u32_e32 v8, s50, v12
	v_max_i32_e32 v8, 0, v8
	v_mov_b32_e32 v9, v4
	v_lshlrev_b64 v[8:9], s12, v[8:9]
	v_lshl_add_u64 v[8:9], s[6:7], 0, v[8:9]
	v_mad_u64_u32 v[10:11], s[10:11], v13, s48, v[8:9]
	v_lshlrev_b64 v[10:11], 9, v[10:11]
	s_lshl_b32 s51, s24, 10
	v_mad_u64_u32 v[8:9], s[10:11], v5, s48, v[8:9]
	v_lshl_add_u64 v[10:11], v[6:7], 0, v[10:11]
	s_add_i32 m0, s62, s51
	v_lshlrev_b64 v[8:9], 9, v[8:9]
	s_add_i32 s17, s63, 16
	global_load_lds_dwordx4 v[10:11], off
	v_lshl_add_u64 v[8:9], v[6:7], 0, v[8:9]
	s_add_i32 m0, s46, s51
	s_lshl_b32 s52, s17, 3
	global_load_lds_dwordx4 v[8:9], off
	v_add_u32_e32 v8, s52, v12
	v_max_i32_e32 v8, 0, v8
	v_mov_b32_e32 v9, v4
	v_lshlrev_b64 v[8:9], s12, v[8:9]
	v_lshl_add_u64 v[8:9], s[6:7], 0, v[8:9]
	v_mad_u64_u32 v[10:11], s[10:11], v13, s48, v[8:9]
	v_lshlrev_b64 v[10:11], 9, v[10:11]
	s_lshl_b32 s53, s17, 10
	v_mad_u64_u32 v[8:9], s[10:11], v5, s48, v[8:9]
	v_lshl_add_u64 v[10:11], v[6:7], 0, v[10:11]
	s_add_i32 m0, s62, s53
	v_lshlrev_b64 v[8:9], 9, v[8:9]
	s_add_i32 s10, s63, 24
	global_load_lds_dwordx4 v[10:11], off
	v_lshl_add_u64 v[8:9], v[6:7], 0, v[8:9]
	s_add_i32 m0, s46, s53
	s_lshl_b32 s54, s10, 3
	global_load_lds_dwordx4 v[8:9], off
	v_add_u32_e32 v8, s54, v12
	v_max_i32_e32 v8, 0, v8
	v_mov_b32_e32 v9, v4
	v_lshlrev_b64 v[8:9], s12, v[8:9]
	v_lshl_add_u64 v[8:9], s[6:7], 0, v[8:9]
	v_mad_u64_u32 v[10:11], s[6:7], v13, s48, v[8:9]
	v_lshlrev_b64 v[10:11], 9, v[10:11]
	s_lshl_b32 s55, s10, 10
	v_mad_u64_u32 v[8:9], s[6:7], v5, s48, v[8:9]
	v_lshl_add_u64 v[10:11], v[6:7], 0, v[10:11]
	s_add_i32 m0, s62, s55
	v_lshlrev_b64 v[8:9], 9, v[8:9]
	s_lshr_b32 s6, s16, 8
	s_lshl_b32 s56, s63, 4
	v_and_b32_e32 v2, 15, v1
	global_load_lds_dwordx4 v[10:11], off
	v_lshl_add_u64 v[6:7], v[6:7], 0, v[8:9]
	s_add_i32 m0, s46, s55
	s_mul_i32 s6, s6, 0x8100
	s_add_i32 s14, s14, s56
	global_load_lds_dwordx4 v[6:7], off
	s_ashr_i32 s7, s6, 31
	v_or_b32_e32 v6, s14, v2
	v_ashrrev_i32_e32 v7, 31, v6
	s_add_u32 s4, s4, s6
	v_lshrrev_b32_e32 v3, 4, v130
	v_lshlrev_b64 v[6:7], s12, v[6:7]
	s_addc_u32 s5, s5, s7
	s_or_b32 s4, s4, s13
	v_lshlrev_b32_e32 v31, 3, v3
	v_lshl_add_u64 v[6:7], s[4:5], 0, v[6:7]
	s_and_b32 s4, s15, 0xc0
	v_lshlrev_b64 v[6:7], 9, v[6:7]
	v_or_b32_e32 v5, s4, v31
	v_lshl_add_u64 v[6:7], s[30:31], 0, v[6:7]
	v_lshlrev_b32_e32 v8, 1, v5
	v_mov_b32_e32 v9, v4
	v_lshl_add_u64 v[6:7], v[6:7], 0, v[8:9]
	global_load_dwordx4 v[18:21], v[6:7], off
	global_load_dwordx4 v[14:17], v[6:7], off offset:64
	s_movk_i32 s22, 0x81
	s_mov_b32 s41, 0
	v_and_b32_e32 v5, 7, v1
	v_cmp_gt_i32_e64 s[4:5], s22, v1
	v_mov_b32_e32 v71, 0
	s_and_saveexec_b64 s[6:7], s[4:5]
	s_cbranch_execz .LBB0_1480
	s_lshl_b32 s9, s9, 3
	s_or_b32 s8, s9, s8
	s_mulk_i32 s8, 0x84
	v_add_u32_e32 v6, s8, v1
	v_ashrrev_i32_e32 v7, 31, v6
	v_lshl_add_u64 v[6:7], v[6:7], 2, s[38:39]
	global_load_dword v71, v[6:7], off

; __global__ void __launch_bounds__(NWAVES * 64, 2) fwd(Args args_unused) {
;     ...
;                 __syncthreads();
;             }
.LBB0_1519:
	s_cmp_eq_u32 s98, 1
	s_cbranch_scc1 .Lro_fin_0
	s_mov_b32 s98, 1
	s_branch .Lro_again_0

; #define SUB(k, bit) (!(kargs()->li == 1 && (k) == lo) || ((kargs()->submask >> (bit)) & 1u))
; __global__ void __launch_bounds__(NWAVES * 64, 2) fwd(Args args_unused) {
;     ...
;         if (IN(pb + 3)) {
;             PH_PTRS PH_LAYER
;             if (SUB(pb + 3, 0)) {
;                 const int nitems = (M / 16) * 5;
; #pragma unroll 1
;                 for (int it = gw; it < nitems; it += NGW) {
;                     const int seg = it / 5, c = (it - seg * 5) * 64 + lane;
;                     if (c >= 192 && seg * 16 < NPROMPT) continue;
;                     const bool isB = c < 192; const int col = isB ? 8 * c : 8 * (c - 192); const int zc = isB ? ZXBC + col : ZXC + col; const int nch = isB ? 1536 : 1024;
;                     const float* cwp = (isB ? A->in[I_CBW] + (size_t)l * 4 * 1536 : A->in[I_CCW] + (size_t)l * 4 * 1024) + col;
;                     const float* cbp = (isB ? A->in[I_CBB] + (size_t)l * 1536 : A->in[I_CCB] + (size_t)l * 1024) + col;
.Lro_again_1:
	s_cmp_lt_i32 s84, 17
	s_cselect_b64 s[0:1], -1, 0
	s_cmp_gt_i32 s85, 16
	s_waitcnt lgkmcnt(0)
	s_cselect_b64 s[4:5], -1, 0
	s_and_b64 s[0:1], s[0:1], s[4:5]
	s_andn2_b64 vcc, exec, s[0:1]
	s_cbranch_vccnz .LBB0_3545
	s_mov_b64 s[26:27], s[82:83]
	s_load_dwordx2 s[28:29], s[26:27], 0x148
	s_mov_b32 s62, 0
	s_mov_b32 s3, s2
	s_load_dword s64, s[82:83], 0x168
	v_readlane_b32 s33, v254, 3
	v_mov_b32_e32 v1, v0
	s_waitcnt lgkmcnt(0)
	s_lshl_b32 s4, s33, 3
	v_readfirstlane_b32 s61, v1
	s_ashr_i32 s63, s61, 6
	s_lshl_b32 s3, s64, 3
	s_add_i32 s60, s63, s4
	s_add_u32 s30, s28, 0x1d200000
	s_addc_u32 s31, s29, 0
	s_cmpk_gt_i32 s60, 0x284f
	v_and_b32_e32 v130, 63, v1
	s_cselect_b32 s99, 1, 0
	s_cmp_eq_u32 s98, 0
	s_cbranch_scc1 .LBB0_3502
	s_cmp_lg_u32 s99, 0
	s_cbranch_scc1 .LBB0_3502
	s_add_u32 s8, s28, 0x4d800000
	s_addc_u32 s9, s29, 0
	s_add_u32 s10, s28, 0x53900000
	s_addc_u32 s11, s29, 0
	s_lshl_b32 s4, s33, 9
	s_lshl_b32 s5, s63, 6
	s_add_i32 s4, s4, s5
	v_or_b32_e32 v131, s4, v130
	v_lshlrev_b32_e32 v140, 3, v131
	s_lshl_b32 s65, s64, 12
	s_lshl_b32 s66, s64, 9
	s_movk_i32 s67, 0xc0
	s_movk_i32 s68, 0xbf
	v_mov_b32_e32 v133, 0
	v_mov_b32_e32 v141, 0x400
	v_mov_b32_e32 v142, 0x600
	v_mov_b32_e32 v143, 0x1c00
	v_mov_b32_e32 v144, 0x1600
	v_mov_b32_e32 v145, 0xd8
	v_mov_b32_e32 v146, 0xa0
	v_mov_b32_e32 v147, 0x4000
	v_mov_b32_e32 v148, 0x6000
	v_mov_b32_e32 v149, 0xe0
	v_mov_b32_e32 v150, 0xa8
	v_mov_b32_e32 v151, 0x1000
	v_mov_b32_e32 v152, 0x1800
	v_mov_b32_e32 v153, 0xc00
	s_mov_b32 s69, s60
	s_branch .LBB0_3393

; #define LAS __attribute__((address_space(3)))
; __global__ void __launch_bounds__(NWAVES * 64, 2) fwd(Args args_unused) {
;     ...
;                 LAS unsigned char* KB0 = lds; LAS unsigned char* VB0 = lds + 65536; LAS float* bsm = (LAS float*)(lds + 131072);
;                 const int qq = lane & 15, q4 = lane >> 4, w = wave;
;                 constexpr int NUN = 16 * 3 * 8 * 16;
;     ...
;                 bf16x8 qn[2] = {(bf16x8){0, 0, 0, 0, 0, 0, 0, 0}, (bf16x8){0, 0, 0, 0, 0, 0, 0, 0}}; float bnx = 0.f;
;                 __syncthreads();
;                 if (vcu < NUN) ATT_ISSUE(vcu, 0, qn);
.LBB0_3502:
	s_cmp_eq_u32 s98, 1
	s_cbranch_scc1 .Lro_fin_1
	s_add_u32 s34, s28, 0xb800000
	s_addc_u32 s35, s29, 0
	s_add_u32 s36, s28, 0x67c00000
	s_addc_u32 s37, s29, 0
	s_cmpk_gt_i32 s33, 0x17ff
	s_waitcnt vmcnt(0)
	s_barrier
	s_cbranch_scc1 .LBB0_3521
	s_add_i32 s46, s62, 0x10000
	s_add_u32 s38, s28, 0xb000000
	s_addc_u32 s39, s29, 0
	s_ashr_i32 s4, s33, 7
	s_mul_hi_i32 s6, s4, 0x55555556
	s_lshr_b32 s7, s6, 31
	s_add_i32 s6, s6, s7
	s_mul_i32 s6, s6, 3
	s_sub_i32 s9, s4, s6
	s_mul_hi_i32 s4, s33, 0x2aaaaaab
	s_lshr_b32 s6, s4, 31
	s_ashr_i32 s4, s4, 6
	s_and_b32 s5, s33, 15
	s_bfe_u32 s8, s33, 0x30004
	s_add_i32 s4, s4, s6
	s_cmp_eq_u32 s9, 1
	s_cselect_b32 s6, 2, 4
	s_cmp_lg_u32 s9, 0
	s_cselect_b32 s12, s6, 0
	s_sub_i32 s7, 4, s12
	v_lshrrev_b32_e32 v4, 3, v130
	s_lshr_b32 s6, 16, s12
	s_lshr_b32 s13, s5, s7
	v_bitop3_b32 v5, v4, v1, 7 bitop3:0x78
	s_lshl_b32 s10, s9, 9
	s_lshl_b32 s15, s8, 6
	s_mul_i32 s6, s13, s6
	s_or_b32 s16, s10, s15
	v_lshlrev_b32_e32 v29, 3, v5
	s_sub_i32 s5, s5, s6
	v_or_b32_e32 v5, s16, v29
	s_lshl_b32 s14, s5, 7
	v_or_b32_e32 v28, 0xffffff80, v4
	v_add_u32_e32 v4, 0x600, v5
	v_mov_b32_e32 v30, 0xf8
	v_add_u32_e32 v12, s14, v28
	v_lshrrev_b32_e32 v13, 8, v4
	v_bitop3_b32 v4, s16, v30, v29 bitop3:0xc8
	s_lshl_b32 s47, s63, 3
	s_ashr_i32 s5, s4, 31
	v_lshlrev_b32_e32 v6, 1, v4
	v_mov_b32_e32 v4, 0
	v_add_u32_e32 v8, s47, v12
	s_lshl_b64 s[4:5], s[4:5], 11
	v_max_i32_e32 v8, 0, v8
	v_mov_b32_e32 v9, v4
	s_or_b32 s6, s4, s13
	s_mov_b32 s7, s5
	v_lshlrev_b64 v[8:9], s12, v[8:9]
	v_add_u32_e32 v5, 0xc00, v5
	v_lshl_add_u64 v[8:9], s[6:7], 0, v[8:9]
	s_mov_b32 s48, 0x8100
	v_mov_b32_e32 v7, v4
	v_lshrrev_b32_e32 v5, 8, v5
	v_mad_u64_u32 v[10:11], s[10:11], v13, s48, v[8:9]
	v_lshl_add_u64 v[6:7], s[30:31], 0, v[6:7]
	v_lshlrev_b64 v[10:11], 9, v[10:11]
	s_lshl_b32 s49, s63, 10
	v_mad_u64_u32 v[8:9], s[10:11], v5, s48, v[8:9]
	v_lshl_add_u64 v[10:11], v[6:7], 0, v[10:11]
	s_add_i32 m0, s62, s49
	v_lshlrev_b64 v[8:9], 9, v[8:9]
	s_add_i32 s24, s63, 8
	global_load_lds_dwordx4 v[10:11], off
	v_lshl_add_u64 v[8:9], v[6:7], 0, v[8:9]
	s_add_i32 m0, s46, s49
	s_lshl_b32 s50, s24, 3
	global_load_lds_dwordx4 v[8:9], off
	v_add_u32_e32 v8, s50, v12
	v_max_i32_e32 v8, 0, v8
	v_mov_b32_e32 v9, v4
	v_lshlrev_b64 v[8:9], s12, v[8:9]
	v_lshl_add_u64 v[8:9], s[6:7], 0, v[8:9]
	v_mad_u64_u32 v[10:11], s[10:11], v13, s48, v[8:9]
	v_lshlrev_b64 v[10:11], 9, v[10:11]
	s_lshl_b32 s51, s24, 10
	v_mad_u64_u32 v[8:9], s[10:11], v5, s48, v[8:9]
	v_lshl_add_u64 v[10:11], v[6:7], 0, v[10:11]
	s_add_i32 m0, s62, s51
	v_lshlrev_b64 v[8:9], 9, v[8:9]
	s_add_i32 s17, s63, 16
	global_load_lds_dwordx4 v[10:11], off
	v_lshl_add_u64 v[8:9], v[6:7], 0, v[8:9]
	s_add_i32 m0, s46, s51
	s_lshl_b32 s52, s17, 3
	global_load_lds_dwordx4 v[8:9], off
	v_add_u32_e32 v8, s52, v12
	v_max_i32_e32 v8, 0, v8
	v_mov_b32_e32 v9, v4
	v_lshlrev_b64 v[8:9], s12, v[8:9]
	v_lshl_add_u64 v[8:9], s[6:7], 0, v[8:9]
	v_mad_u64_u32 v[10:11], s[10:11], v13, s48, v[8:9]
	v_lshlrev_b64 v[10:11], 9, v[10:11]
	s_lshl_b32 s53, s17, 10
	v_mad_u64_u32 v[8:9], s[10:11], v5, s48, v[8:9]
	v_lshl_add_u64 v[10:11], v[6:7], 0, v[10:11]
	s_add_i32 m0, s62, s53
	v_lshlrev_b64 v[8:9], 9, v[8:9]
	s_add_i32 s10, s63, 24
	global_load_lds_dwordx4 v[10:11], off
	v_lshl_add_u64 v[8:9], v[6:7], 0, v[8:9]
	s_add_i32 m0, s46, s53
	s_lshl_b32 s54, s10, 3
	global_load_lds_dwordx4 v[8:9], off
	v_add_u32_e32 v8, s54, v12
	v_max_i32_e32 v8, 0, v8
	v_mov_b32_e32 v9, v4
	v_lshlrev_b64 v[8:9], s12, v[8:9]
	v_lshl_add_u64 v[8:9], s[6:7], 0, v[8:9]
	v_mad_u64_u32 v[10:11], s[6:7], v13, s48, v[8:9]
	v_lshlrev_b64 v[10:11], 9, v[10:11]
	s_lshl_b32 s55, s10, 10
	v_mad_u64_u32 v[8:9], s[6:7], v5, s48, v[8:9]
	v_lshl_add_u64 v[10:11], v[6:7], 0, v[10:11]
	s_add_i32 m0, s62, s55
	v_lshlrev_b64 v[8:9], 9, v[8:9]
	s_lshr_b32 s6, s16, 8
	s_lshl_b32 s56, s63, 4
	v_and_b32_e32 v2, 15, v1
	global_load_lds_dwordx4 v[10:11], off
	v_lshl_add_u64 v[6:7], v[6:7], 0, v[8:9]
	s_add_i32 m0, s46, s55
	s_mul_i32 s6, s6, 0x8100
	s_add_i32 s14, s14, s56
	global_load_lds_dwordx4 v[6:7], off
	s_ashr_i32 s7, s6, 31
	v_or_b32_e32 v6, s14, v2
	v_ashrrev_i32_e32 v7, 31, v6
	s_add_u32 s4, s4, s6
	v_lshrrev_b32_e32 v3, 4, v130
	v_lshlrev_b64 v[6:7], s12, v[6:7]
	s_addc_u32 s5, s5, s7
	s_or_b32 s4, s4, s13
	v_lshlrev_b32_e32 v31, 3, v3
	v_lshl_add_u64 v[6:7], s[4:5], 0, v[6:7]
	s_and_b32 s4, s15, 0xc0
	v_lshlrev_b64 v[6:7], 9, v[6:7]
	v_or_b32_e32 v5, s4, v31
	v_lshl_add_u64 v[6:7], s[30:31], 0, v[6:7]
	v_lshlrev_b32_e32 v8, 1, v5
	v_mov_b32_e32 v9, v4
	v_lshl_add_u64 v[6:7], v[6:7], 0, v[8:9]
	global_load_dwordx4 v[18:21], v[6:7], off
	global_load_dwordx4 v[14:17], v[6:7], off offset:64
	s_movk_i32 s22, 0x81
	s_mov_b32 s41, 0
	v_and_b32_e32 v5, 7, v1
	v_cmp_gt_i32_e64 s[4:5], s22, v1
	v_mov_b32_e32 v71, 0
	s_and_saveexec_b64 s[6:7], s[4:5]
	s_cbranch_execz .LBB0_3505
	s_lshl_b32 s9, s9, 3
	s_or_b32 s8, s9, s8
	s_mulk_i32 s8, 0x84
	v_add_u32_e32 v6, s8, v1
	v_ashrrev_i32_e32 v7, 31, v6
	v_lshl_add_u64 v[6:7], v[6:7], 2, s[38:39]
	global_load_dword v71, v[6:7], off

; __global__ void __launch_bounds__(NWAVES * 64, 2) fwd(Args args_unused) {
	.amdhsa_kernel _Z3fwd4Args
		.amdhsa_group_segment_fixed_size 0
		.amdhsa_private_segment_fixed_size 0
		.amdhsa_kernarg_size 616
		.amdhsa_user_sgpr_count 2
		.amdhsa_user_sgpr_dispatch_ptr 0
		.amdhsa_user_sgpr_queue_ptr 0
		.amdhsa_user_sgpr_kernarg_segment_ptr 1
		.amdhsa_user_sgpr_dispatch_id 0
		.amdhsa_user_sgpr_kernarg_preload_length 0
		.amdhsa_user_sgpr_kernarg_preload_offset 0
		.amdhsa_user_sgpr_private_segment_size 0
		.amdhsa_uses_dynamic_stack 0
		.amdhsa_enable_private_segment 0
		.amdhsa_system_sgpr_workgroup_id_x 1
		.amdhsa_system_sgpr_workgroup_id_y 0
		.amdhsa_system_sgpr_workgroup_id_z 0
		.amdhsa_system_sgpr_workgroup_info 0
		.amdhsa_system_vgpr_workitem_id 0
		.amdhsa_next_free_vgpr 255
		.amdhsa_next_free_sgpr 100
		.amdhsa_accum_offset 256
		.amdhsa_reserve_vcc 1
		.amdhsa_float_round_mode_32 0
		.amdhsa_float_round_mode_16_64 0
		.amdhsa_float_denorm_mode_32 3
		.amdhsa_float_denorm_mode_16_64 3
		.amdhsa_dx10_clamp 1
		.amdhsa_ieee_mode 1
		.amdhsa_fp16_overflow 0
		.amdhsa_tg_split 0
		.amdhsa_exception_fp_ieee_invalid_op 0
		.amdhsa_exception_fp_denorm_src 0
		.amdhsa_exception_fp_ieee_div_zero 0
		.amdhsa_exception_fp_ieee_overflow 0
		.amdhsa_exception_fp_ieee_underflow 0
		.amdhsa_exception_fp_ieee_inexact 0
		.amdhsa_exception_int_div_zero 0
	.end_amdhsa_kernel
